# barrier between out-proj(l0) and in-proj(l1) narrowed to the 4-workgroup panel group
# speedup vs baseline: 1.0242x; 1.0019x over previous
; __device__ __forceinline__ unsigned xb_ld(unsigned* p)              { return __hip_atomic_load(p, __ATOMIC_RELAXED, __HIP_MEMORY_SCOPE_AGENT); }
; __device__ __forceinline__ unsigned xb_add(unsigned* p, unsigned v) { return __hip_atomic_fetch_add(p, v, __ATOMIC_RELAXED, __HIP_MEMORY_SCOPE_AGENT); }
; #define XB_SPIN(cond, bar) do { unsigned _sp = 0; while (cond) { __builtin_amdgcn_s_sleep(1); \
;     if ((++_sp & 255u) == 0u) { if (xb_ld(&(bar)[XB_TMO])) break; if (_sp > XB_SPIN_CAP) { atomicAdd(&(bar)[XB_TMO], 1u); break; } } } } while (0)
; __device__ __forceinline__ void xcd_barrier(const XcdBarrier& b) {
;     asm volatile("s_waitcnt vmcnt(0)" ::: "memory");
;     __syncthreads();
;     if (threadIdx.x == 0) {
;         unsigned* bar = b.bar;
;         __builtin_amdgcn_s_waitcnt(0);
;         unsigned nloc = b.st[0], nx = b.st[1];
;         if (nloc == 0u) { xcd_barrier_complete(bar, b.x, nloc, nx); b.st[0] = nloc; b.st[1] = nx; }
;         const unsigned old = xb_add(&bar[XB_XSUB(b.x)], 1u);
;         const unsigned gen = old / nloc;
;         if (old + 1u == (gen + 1u) * nloc) {
;             __builtin_amdgcn_fence(__ATOMIC_RELEASE, "agent");
;             asm volatile("s_waitcnt vmcnt(0)" ::: "memory");
;             const unsigned og = xb_add(&bar[XB_TOP], 1u);
;             const unsigned tg = og / nx;
;             if (og + 1u == (tg + 1u) * nx) xb_add(&bar[XB_TOPGEN], 1u);
;             else XB_SPIN(xb_ld(&bar[XB_TOPGEN]) == tg, bar);
;             __builtin_amdgcn_fence(__ATOMIC_ACQUIRE, "agent");
;             xb_add(&bar[XB_XGEN(b.x)], 1u);
;             asm volatile("s_waitcnt vmcnt(0)" ::: "memory");
;         } else {
;             XB_SPIN(xb_ld(&bar[XB_XGEN(b.x)]) == gen, bar);
;             __builtin_amdgcn_fence(__ATOMIC_ACQUIRE, "agent");
;             asm volatile("s_waitcnt vmcnt(0)" ::: "memory");
;         }
;     }
;     __syncthreads();
; }
.Lbbsb:
	s_waitcnt vmcnt(0) lgkmcnt(0)
	s_barrier
	s_add_u32 s8, s78, 0xfc00000
	s_addc_u32 s9, s79, 0
	s_and_b32 s5, s2, 7
	s_lshl_b32 s5, s5, 6
	s_add_i32 s101, s101, 1
	s_and_b32 s6, s101, 0xffff
	s_lshl_b32 s6, s6, 5
	v_cmp_eq_u32_e32 vcc, 0, v178
	s_and_saveexec_b64 s[14:15], vcc
	s_cbranch_execz .Lbbsb_join
	v_mov_b32_e32 v0, s5
	v_mov_b32_e32 v2, 1
	s_cmp_lg_u32 s100, 0
	s_cbranch_scc1 .Lbbsb_known
	global_load_dword v1, v0, s[8:9] offset:32 sc1
	s_waitcnt vmcnt(0)
	v_readfirstlane_b32 s16, v1
	s_bcnt1_i32_b32 s16, s16
	s_cmp_eq_u32 s16, 1
	s_cselect_b32 s100, 1, 2

; __device__ __forceinline__ unsigned xb_ld(unsigned* p)              { return __hip_atomic_load(p, __ATOMIC_RELAXED, __HIP_MEMORY_SCOPE_AGENT); }
; __device__ __forceinline__ unsigned xb_add(unsigned* p, unsigned v) { return __hip_atomic_fetch_add(p, v, __ATOMIC_RELAXED, __HIP_MEMORY_SCOPE_AGENT); }
; #define XB_SPIN(cond, bar) do { unsigned _sp = 0; while (cond) { __builtin_amdgcn_s_sleep(1); \
;     if ((++_sp & 255u) == 0u) { if (xb_ld(&(bar)[XB_TMO])) break; if (_sp > XB_SPIN_CAP) { atomicAdd(&(bar)[XB_TMO], 1u); break; } } } } while (0)
; __device__ __forceinline__ void xcd_barrier(const XcdBarrier& b) {
;     asm volatile("s_waitcnt vmcnt(0)" ::: "memory");
;     __syncthreads();
;     if (threadIdx.x == 0) {
;         unsigned* bar = b.bar;
;         __builtin_amdgcn_s_waitcnt(0);
;         unsigned nloc = b.st[0], nx = b.st[1];
;         if (nloc == 0u) { xcd_barrier_complete(bar, b.x, nloc, nx); b.st[0] = nloc; b.st[1] = nx; }
;         const unsigned old = xb_add(&bar[XB_XSUB(b.x)], 1u);
;         const unsigned gen = old / nloc;
;         if (old + 1u == (gen + 1u) * nloc) {
;             __builtin_amdgcn_fence(__ATOMIC_RELEASE, "agent");
;             asm volatile("s_waitcnt vmcnt(0)" ::: "memory");
;             const unsigned og = xb_add(&bar[XB_TOP], 1u);
;             const unsigned tg = og / nx;
;             if (og + 1u == (tg + 1u) * nx) xb_add(&bar[XB_TOPGEN], 1u);
;             else XB_SPIN(xb_ld(&bar[XB_TOPGEN]) == tg, bar);
;             __builtin_amdgcn_fence(__ATOMIC_ACQUIRE, "agent");
;             xb_add(&bar[XB_XGEN(b.x)], 1u);
;             asm volatile("s_waitcnt vmcnt(0)" ::: "memory");
;         } else {
;             XB_SPIN(xb_ld(&bar[XB_XGEN(b.x)]) == gen, bar);
;             __builtin_amdgcn_fence(__ATOMIC_ACQUIRE, "agent");
;             asm volatile("s_waitcnt vmcnt(0)" ::: "memory");
;         }
;     }
;     __syncthreads();
; }
.Lpbsb4:
	s_waitcnt vmcnt(0) lgkmcnt(0)
	s_barrier
	s_add_u32 s8, s78, 0xfc00000
	s_addc_u32 s9, s79, 0
	s_and_b32 s5, s2, 7
	s_lshl_b32 s5, s5, 3
	s_bfe_u32 s6, s2, 0x30003
	s_or_b32 s5, s5, s6
	s_lshl_b32 s5, s5, 2
	s_add_i32 s5, s5, 640
	s_add_i32 s101, s101, 0x10000
	s_lshr_b32 s6, s101, 16
	s_lshl_b32 s6, s6, 2
	v_cmp_eq_u32_e32 vcc, 0, v178
	s_and_saveexec_b64 s[14:15], vcc
	s_cbranch_execz .Lpbsb4_join
	v_mov_b32_e32 v0, s5
	v_mov_b32_e32 v2, 1
	s_cmp_eq_u32 s100, 1
	s_cbranch_scc1 .Lpbsb4_fast
	buffer_wbl2 sc1
	s_waitcnt vmcnt(0)
